# MLA loop: softmax row-max via v_max3 tree + permlane16/32 swaps instead of ds_bpermute (LDS round trips), explicit lgkmcnt before PV
# speedup vs baseline: 1.0527x; 1.0072x over previous
.LBB0_1376:
	s_or_b64 exec, exec, s[0:1]
	s_and_b32 s0, s27, 1
	s_mul_i32 s1, s0, 0x3400
	v_add_u32_e32 v124, s1, v175
	ds_read_b128 v[76:79], v124
	ds_read_b128 v[88:91], v124 offset:64
	v_xor_b32_e32 v80, 0x80000000, v159
	v_xor_b32_e32 v84, 0x80000000, v158
	v_mov_b32_e32 v81, v80
	v_mov_b32_e32 v82, v80
	v_mov_b32_e32 v83, v80
	v_mov_b32_e32 v85, v84
	v_mov_b32_e32 v86, v84
	v_mov_b32_e32 v87, v84
	s_waitcnt lgkmcnt(1)
	v_mfma_f32_16x16x32_bf16 v[92:95], v[76:79], v[20:23], v[80:83]
	ds_read_b128 v[96:99], v124 offset:3328
	ds_read_b128 v[100:103], v124 offset:128
	ds_read_b128 v[108:111], v124 offset:6656
	ds_read_b128 v[112:115], v124 offset:6720
	ds_read_b128 v[120:123], v124 offset:9984
	ds_read_b128 v[182:185], v124 offset:6784
	v_mfma_f32_16x16x32_bf16 v[76:79], v[76:79], v[24:27], v[84:87]
	s_mul_i32 s1, s0, 0x2800
	s_waitcnt lgkmcnt(5)
	v_mfma_f32_16x16x32_bf16 v[104:107], v[96:99], v[20:23], v[80:83]
	v_mfma_f32_16x16x32_bf16 v[96:99], v[96:99], v[24:27], v[84:87]
	s_waitcnt lgkmcnt(3)
	v_mfma_f32_16x16x32_bf16 v[116:119], v[108:111], v[20:23], v[80:83]
	v_mfma_f32_16x16x32_bf16 v[108:111], v[108:111], v[24:27], v[84:87]
	s_waitcnt lgkmcnt(1)
	v_mfma_f32_16x16x32_bf16 v[80:83], v[120:123], v[20:23], v[80:83]
	v_mfma_f32_16x16x32_bf16 v[84:87], v[120:123], v[24:27], v[84:87]
	v_mfma_f32_16x16x32_bf16 v[92:95], v[88:91], v[12:15], v[92:95]
	v_mfma_f32_16x16x32_bf16 v[76:79], v[88:91], v[16:19], v[76:79]
	ds_read_b128 v[88:91], v124 offset:3392
	ds_read_b128 v[120:123], v124 offset:3456
	s_waitcnt lgkmcnt(1)
	v_mfma_f32_16x16x32_bf16 v[104:107], v[88:91], v[12:15], v[104:107]
	v_mfma_f32_16x16x32_bf16 v[88:91], v[88:91], v[16:19], v[96:99]
	s_nop 2
	ds_read_b128 v[96:99], v124 offset:10048
	ds_read_b128 v[190:193], v124 offset:10112
	s_waitcnt lgkmcnt(1)
	v_mfma_f32_16x16x32_bf16 v[194:197], v[96:99], v[12:15], v[80:83]
	s_nop 2
	v_add_u32_e32 v80, s43, v178
	v_ashrrev_i32_e32 v81, 31, v80
	v_mfma_f32_16x16x32_bf16 v[128:131], v[100:103], v[4:7], v[76:79]
	v_add_u32_e32 v82, s1, v176
	s_nop 1
	v_lshlrev_b64 v[76:77], 11, v[80:81]
	v_lshl_add_u64 v[76:77], v[160:161], 0, v[76:77]
	global_load_dwordx4 v[76:79], v[76:77], off offset:128
	v_mfma_f32_16x16x32_bf16 v[116:119], v[112:115], v[12:15], v[116:119]
	v_mfma_f32_16x16x32_bf16 v[186:189], v[112:115], v[16:19], v[108:111]
	v_mfma_f32_16x16x32_bf16 v[198:201], v[96:99], v[16:19], v[84:87]
	ds_read_b64_tr_b16 v[124:125], v82 offset:26624
	ds_read_b64_tr_b16 v[112:113], v82 offset:26656
	ds_read_b64_tr_b16 v[108:109], v82 offset:26688
	ds_read_b64_tr_b16 v[96:97], v82 offset:26720
	ds_read_b64_tr_b16 v[126:127], v82 offset:29184
	ds_read_b64_tr_b16 v[114:115], v82 offset:29216
	ds_read_b64_tr_b16 v[110:111], v82 offset:29248
	ds_read_b64_tr_b16 v[98:99], v82 offset:29280
	v_mfma_f32_16x16x32_bf16 v[136:139], v[100:103], v[8:11], v[92:95]
	v_mfma_f32_16x16x32_bf16 v[132:135], v[120:123], v[4:7], v[88:91]
	s_nop 1
	ds_read_b64_tr_b16 v[92:93], v82 offset:31744
	ds_read_b64_tr_b16 v[88:89], v82 offset:31776
	ds_read_b64_tr_b16 v[84:85], v82 offset:31808
	ds_read_b64_tr_b16 v[80:81], v82 offset:31840
	ds_read_b64_tr_b16 v[94:95], v82 offset:34304
	ds_read_b64_tr_b16 v[90:91], v82 offset:34336
	ds_read_b64_tr_b16 v[86:87], v82 offset:34368
	ds_read_b64_tr_b16 v[82:83], v82 offset:34400
	v_mfma_f32_16x16x32_bf16 v[140:143], v[120:123], v[8:11], v[104:107]
	v_mfma_f32_16x16x32_bf16 v[116:119], v[182:185], v[8:11], v[116:119]
	v_mfma_f32_16x16x32_bf16 v[100:103], v[182:185], v[4:7], v[186:189]
	s_waitcnt lgkmcnt(14)
	v_mfma_f32_16x16x32_bf16 v[120:123], v[190:193], v[8:11], v[194:197]
	v_mfma_f32_16x16x32_bf16 v[104:107], v[190:193], v[4:7], v[198:201]
	v_max3_f32 v181, v136, v137, v138
	v_max3_f32 v183, v128, v129, v130
	v_max3_f32 v184, v131, v132, v133
	v_max3_f32 v181, v181, v139, v140
	v_max3_f32 v183, v183, v134, v135
	v_max3_f32 v181, v181, v141, v142
	v_max3_f32 v182, v143, v116, v117
	v_max3_f32 v184, v184, v100, v101
	v_max3_f32 v182, v182, v118, v119
	v_max3_f32 v184, v184, v102, v103
	v_max3_f32 v181, v181, v120, v121
	v_max3_f32 v182, v182, v122, v123
	v_max3_f32 v183, v183, v104, v105
	v_max3_f32 v184, v184, v106, v107
	v_max_f32_e32 v181, v181, v182
	v_max_f32_e32 v183, v183, v184
	v_mov_b32_e32 v182, v181
	v_mov_b32_e32 v184, v183
	s_nop 1
	v_permlane16_swap_b32_e32 v181, v182
	v_permlane16_swap_b32_e32 v183, v184
	v_max_f32_e32 v181, v181, v182
	v_max_f32_e32 v183, v183, v184
	v_mov_b32_e32 v182, v181
	v_mov_b32_e32 v184, v183
	s_nop 1
	v_permlane32_swap_b32_e32 v181, v182
	v_permlane32_swap_b32_e32 v183, v184
	v_max_f32_e32 v182, v181, v182
	v_max_f32_e32 v181, v183, v184
	v_max_f32_e32 v183, v182, v181
	v_cmp_lt_f32_e32 vcc, s36, v183
	s_cbranch_vccz .LBB0_1378
	v_max_f32_e32 v182, v182, v182
	v_max_f32_e32 v183, 0, v182
	v_exp_f32_e64 v182, -v183
	v_max_f32_e32 v181, v181, v181
	v_sub_f32_e32 v136, v136, v183
	v_sub_f32_e32 v137, v137, v183
	v_pk_mul_f32 v[70:71], v[70:71], v[182:183] op_sel_hi:[1,0]
	v_pk_mul_f32 v[68:69], v[68:69], v[182:183] op_sel_hi:[1,0]
	v_pk_mul_f32 v[62:63], v[62:63], v[182:183] op_sel_hi:[1,0]
	v_pk_mul_f32 v[60:61], v[60:61], v[182:183] op_sel_hi:[1,0]
	v_pk_mul_f32 v[54:55], v[54:55], v[182:183] op_sel_hi:[1,0]
	v_pk_mul_f32 v[52:53], v[52:53], v[182:183] op_sel_hi:[1,0]
	v_pk_mul_f32 v[46:47], v[46:47], v[182:183] op_sel_hi:[1,0]
	v_pk_mul_f32 v[44:45], v[44:45], v[182:183] op_sel_hi:[1,0]
	v_pk_mul_f32 v[38:39], v[38:39], v[182:183] op_sel_hi:[1,0]
	v_pk_mul_f32 v[36:37], v[36:37], v[182:183] op_sel_hi:[1,0]
	v_max_f32_e32 v182, 0, v181
	v_exp_f32_e64 v184, -v182
	v_sub_f32_e32 v138, v138, v183
	v_sub_f32_e32 v139, v139, v183
	v_sub_f32_e32 v140, v140, v183
	v_sub_f32_e32 v141, v141, v183
	v_sub_f32_e32 v142, v142, v183
	v_sub_f32_e32 v143, v143, v183
	v_sub_f32_e32 v116, v116, v183
	v_sub_f32_e32 v117, v117, v183
	v_sub_f32_e32 v118, v118, v183
	v_sub_f32_e32 v119, v119, v183
	v_sub_f32_e32 v120, v120, v183
	v_sub_f32_e32 v121, v121, v183
	v_sub_f32_e32 v122, v122, v183
	v_sub_f32_e32 v123, v123, v183
	v_pk_add_f32 v[158:159], v[158:159], v[182:183]
	v_sub_f32_e32 v128, v128, v182
	v_sub_f32_e32 v129, v129, v182
	v_sub_f32_e32 v130, v130, v182
	v_sub_f32_e32 v131, v131, v182
	v_sub_f32_e32 v132, v132, v182
	v_sub_f32_e32 v133, v133, v182
	v_sub_f32_e32 v134, v134, v182
	v_sub_f32_e32 v135, v135, v182
	v_sub_f32_e32 v100, v100, v182
	v_sub_f32_e32 v101, v101, v182
	v_sub_f32_e32 v102, v102, v182
	v_sub_f32_e32 v103, v103, v182
	v_sub_f32_e32 v104, v104, v182
	v_sub_f32_e32 v105, v105, v182
	v_sub_f32_e32 v106, v106, v182
	v_sub_f32_e32 v107, v107, v182
	v_pk_mul_f32 v[66:67], v[66:67], v[184:185] op_sel_hi:[1,0]
	v_pk_mul_f32 v[64:65], v[64:65], v[184:185] op_sel_hi:[1,0]
	v_pk_mul_f32 v[58:59], v[58:59], v[184:185] op_sel_hi:[1,0]
	v_pk_mul_f32 v[56:57], v[56:57], v[184:185] op_sel_hi:[1,0]
	v_pk_mul_f32 v[50:51], v[50:51], v[184:185] op_sel_hi:[1,0]
	v_pk_mul_f32 v[48:49], v[48:49], v[184:185] op_sel_hi:[1,0]
	v_pk_mul_f32 v[42:43], v[42:43], v[184:185] op_sel_hi:[1,0]
	v_pk_mul_f32 v[40:41], v[40:41], v[184:185] op_sel_hi:[1,0]
	v_pk_mul_f32 v[34:35], v[34:35], v[184:185] op_sel_hi:[1,0]
	v_pk_mul_f32 v[32:33], v[32:33], v[184:185] op_sel_hi:[1,0]
.LBB0_1378:
	v_exp_f32_e32 v136, v136
	v_exp_f32_e32 v137, v137
	v_exp_f32_e32 v138, v138
	v_exp_f32_e32 v139, v139
	v_exp_f32_e32 v140, v140
	v_exp_f32_e32 v141, v141
	v_exp_f32_e32 v142, v142
	v_exp_f32_e32 v143, v143
	v_exp_f32_e32 v128, v128
	v_exp_f32_e32 v129, v129
	v_exp_f32_e32 v130, v130
	v_exp_f32_e32 v131, v131
	v_exp_f32_e32 v132, v132
	v_exp_f32_e32 v133, v133
	v_exp_f32_e32 v134, v134
	v_exp_f32_e32 v135, v135
	v_cvt_pk_bf16_f32 v136, v136, v137
	v_cvt_pk_bf16_f32 v137, v138, v139
	v_cvt_pk_bf16_f32 v138, v140, v141
	v_cvt_pk_bf16_f32 v139, v142, v143
	v_cvt_pk_bf16_f32 v128, v128, v129
	v_cvt_pk_bf16_f32 v129, v130, v131
	v_cvt_pk_bf16_f32 v130, v132, v133
	v_cvt_pk_bf16_f32 v131, v134, v135
	s_waitcnt lgkmcnt(0)
	v_mfma_f32_16x16x32_bf16 v[60:63], v[112:115], v[136:139], v[60:63]
	v_exp_f32_e32 v116, v116
	s_xor_b32 s43, s0, 1
	s_mul_i32 s46, s43, 0x3400
	v_mfma_f32_16x16x32_bf16 v[56:59], v[112:115], v[128:131], v[56:59]
	v_exp_f32_e32 v112, v117
	v_exp_f32_e32 v113, v118
	v_exp_f32_e32 v114, v119
	v_exp_f32_e32 v115, v120
	v_exp_f32_e32 v117, v121
	v_mfma_f32_16x16x32_bf16 v[52:55], v[108:111], v[136:139], v[52:55]
	v_exp_f32_e32 v118, v122
	v_mfma_f32_16x16x32_bf16 v[48:51], v[108:111], v[128:131], v[48:51]
	v_cvt_pk_bf16_f32 v108, v116, v112
	v_cvt_pk_bf16_f32 v109, v113, v114
	v_cvt_pk_bf16_f32 v110, v115, v117
	v_mov_b64_e32 v[114:115], s[14:15]
	v_mov_b64_e32 v[112:113], s[12:13]
	v_exp_f32_e32 v111, v123
	v_mfma_f32_16x16x32_bf16 v[44:47], v[96:99], v[136:139], v[44:47]
	v_cvt_pk_bf16_f32 v111, v118, v111
	v_mfma_f32_16x16x32_bf16 v[40:43], v[96:99], v[128:131], v[40:43]
	v_exp_f32_e32 v96, v100
	v_exp_f32_e32 v97, v101
	v_exp_f32_e32 v98, v102
	v_exp_f32_e32 v99, v103
	v_exp_f32_e32 v100, v104
	v_exp_f32_e32 v101, v105
	v_exp_f32_e32 v102, v106
	v_exp_f32_e32 v103, v107
	v_mfma_f32_16x16x32_bf16 v[68:71], v[124:127], v[136:139], v[68:71]
	v_cvt_pk_bf16_f32 v96, v96, v97
	v_cvt_pk_bf16_f32 v97, v98, v99
	v_cvt_pk_bf16_f32 v98, v100, v101
	v_mfma_f32_16x16x32_bf16 v[64:67], v[124:127], v[128:131], v[64:67]
	v_cvt_pk_bf16_f32 v99, v102, v103
	v_mfma_f32_16x16x32_bf16 v[36:39], v[112:115], v[136:139], v[36:39]
	v_mfma_f32_16x16x32_bf16 v[32:35], v[112:115], v[128:131], v[32:35]
	v_mfma_f32_16x16x32_bf16 v[68:71], v[92:95], v[108:111], v[68:71]
	v_mfma_f32_16x16x32_bf16 v[64:67], v[92:95], v[96:99], v[64:67]
	v_mfma_f32_16x16x32_bf16 v[60:63], v[88:91], v[108:111], v[60:63]
	v_mfma_f32_16x16x32_bf16 v[56:59], v[88:91], v[96:99], v[56:59]
	v_mfma_f32_16x16x32_bf16 v[52:55], v[84:87], v[108:111], v[52:55]
	v_mfma_f32_16x16x32_bf16 v[48:51], v[84:87], v[96:99], v[48:51]
	v_mfma_f32_16x16x32_bf16 v[44:47], v[80:83], v[108:111], v[44:47]
	v_mfma_f32_16x16x32_bf16 v[40:43], v[80:83], v[96:99], v[40:43]
	v_lshlrev_b32_e32 v80, 1, v170
	v_add3_u32 v80, s46, v80, v180
	s_waitcnt vmcnt(1)
	ds_write_b128 v80, v[72:75]
	v_mfma_f32_16x16x32_bf16 v[36:39], v[112:115], v[108:111], v[36:39]
	v_mfma_f32_16x16x32_bf16 v[32:35], v[112:115], v[96:99], v[32:35]
	s_and_saveexec_b64 s[0:1], s[6:7]
	s_cbranch_execz .LBB0_1373
	v_lshlrev_b32_e32 v72, 1, v171
	v_add3_u32 v72, s46, v72, v144
	ds_write_b128 v72, v[28:31]
	s_branch .LBB0_1373
